# scans moved onto all 8 waves of the 80 workgroups with the smallest first attention unit; the others start attention without the scan wait
# speedup vs baseline: 1.0154x; 1.0003x over previous
; __global__ void __launch_bounds__(NWAVES * 64, 2) hymba_fwd(Args args) {
;     ...
;             unsigned* scnt = (unsigned*)(ws + WS_SCNT) + layer * 64;
;             { unsigned ndone = 0;
;               if (wave < 2) { for (int t2 = wave * G + vcu; t2 < 512; t2 += 2 * G) { hgrn_scan(pa, t2, lane); ++ndone; } }
;               else if (wave == 2) { for (int t2 = vcu; t2 < 32; t2 += G) { s5_scan(pa, layer, t2, lane); ++ndone; } }
;               if (ndone) { asm volatile("s_waitcnt vmcnt(0)" ::: "memory"); if (lane == 0) (void)__hip_atomic_fetch_add(scnt, ndone, __ATOMIC_RELAXED, __HIP_MEMORY_SCOPE_AGENT); } }
.LBB0_554:
	s_or_b64 exec, exec, s[0:1]
	s_waitcnt lgkmcnt(0)
	s_barrier
	s_mov_b32 s37, 0
	v_readlane_b32 s12, v253, 18
	v_readlane_b32 s0, v252, 0
	s_and_b32 s1, s0, 15
	s_cmp_lt_u32 s1, 11
	s_cbranch_scc1 .LBB0_569
	s_lshr_b32 s0, s0, 4
	s_mul_i32 s0, s0, 5
	s_add_i32 s0, s0, s1
	s_sub_i32 s0, s0, 11
	s_lshl_b32 s0, s0, 3
	s_add_i32 s2, s0, s36
	s_cmpk_gt_u32 s2, 0x21f
	s_cbranch_scc1 .LBB0_569
	s_cmpk_lt_u32 s2, 0x200
	s_cbranch_scc1 .Lmy_sc_h
	s_sub_i32 s3, s2, 0x200
	v_readlane_b32 s0, v254, 44
	s_lshl_b32 s38, s0, 12
	v_readlane_b32 s0, v252, 18
	v_writelane_b32 v255, s74, 7
	v_lshlrev_b32_e32 v220, 2, v140
	v_readlane_b32 s1, v252, 19
	v_writelane_b32 v255, s75, 8
	v_lshlrev_b32_e32 v2, 2, v140
	v_lshl_add_u64 v[0:1], s[0:1], 0, v[220:221]
	s_mov_b32 s39, s3
	s_branch .LBB0_557
.Lmy_sc_h:
	v_and_b32_e32 v6, 3, v141
	v_lshlrev_b32_e32 v220, 2, v140
	s_branch .LBB0_566
